# FFN_IN: bias (shW) loads also issued at k-loop head; epilogue has no loads or vmcnt waits
# baseline (speedup 1.0000x reference)
.LBB0_754:
	v_add_u32_e32 v82, s60, v93
	s_waitcnt lgkmcnt(0)
	v_or_b32_e32 v84, 8, v82
	s_add_i32 s59, s60, 0xffffe000
	s_lshr_b32 s59, s59, 12
	s_mulk_i32 s59, 0x1600
	s_addk_i32 s59, 0x1600
	s_cmp_gt_i32 s4, 63
	s_cselect_b32 s4, s59, 0
	s_lshl_b64 s[60:61], s[4:5], 2
	s_add_u32 s60, s10, s60
	s_addc_u32 s61, s11, s61
	v_or_b32_e32 v120, 1, v82
	v_or_b32_e32 v119, 2, v82
	v_or_b32_e32 v83, 3, v82
	s_add_i32 s3, s3, s33
	s_cmpk_gt_i32 s3, 0x15ff
	v_or_b32_e32 v68, 9, v82
	v_or_b32_e32 v64, 16, v82
	v_mov_b32_e32 v71, v159
	v_or_b32_e32 v85, 10, v82
	v_or_b32_e32 v121, 18, v82
	v_or_b32_e32 v88, 17, v82
	v_or_b32_e32 v86, 24, v82
	v_ashrrev_i32_e32 v87, 31, v86
	v_lshl_add_u64 v[90:91], v[86:87], 2, s[6:7]
	v_or_b32_e32 v87, 11, v82
	v_add_co_u32_e32 v90, vcc, s75, v90
	s_nop 1
	v_addc_co_u32_e32 v91, vcc, 0, v91, vcc
	v_or_b32_e32 v90, 25, v82
	v_mov_b32_e32 v72, v160
	v_mov_b32_e32 v122, v172
	v_mov_b32_e32 v65, v173
	v_mov_b32_e32 v73, v161
	v_mov_b32_e32 v74, v162
	v_mov_b32_e32 v126, v174
	v_mov_b32_e32 v66, v175
	v_mov_b32_e32 v67, v156
	v_mov_b32_e32 v70, v157
	v_mov_b32_e32 v75, v163
	v_mov_b32_e32 v89, v164
	v_mov_b32_e32 v91, v165
	v_mov_b32_e32 v123, v166
	v_mov_b32_e32 v125, v167
	v_mov_b32_e32 v69, v168
	v_or_b32_e32 v124, 19, v82
	v_mov_b32_e32 v132, v158
	v_mov_b32_e32 v127, v169
	v_mov_b32_e32 v129, v170
	v_mov_b32_e32 v131, v171
	v_or_b32_e32 v128, 26, v82
	v_or_b32_e32 v130, 27, v82
	v_fma_f32 v48, v48, v67, v122
	v_fma_f32 v49, v49, v70, v122
	v_fma_f32 v32, v32, v67, v65
	v_fma_f32 v33, v33, v70, v65
	v_fma_f32 v34, v34, v132, v65
	v_fma_f32 v35, v35, v71, v65
	v_fma_f32 v36, v36, v72, v65
	v_fma_f32 v37, v37, v73, v65
	v_fma_f32 v38, v38, v74, v65
	v_fma_f32 v39, v39, v75, v65
	v_fma_f32 v40, v40, v89, v65
	v_fma_f32 v41, v41, v91, v65
	v_fma_f32 v42, v42, v123, v65
	v_fma_f32 v43, v43, v125, v65
	v_fma_f32 v44, v44, v69, v65
	v_fma_f32 v45, v45, v127, v65
	v_fma_f32 v46, v46, v129, v65
	v_fmac_f32_e32 v65, v47, v131
	v_fma_f32 v47, v0, v67, v66
	v_mul_f32_e32 v0, 0xbfb8aa3b, v48
	v_fma_f32 v16, v16, v67, v126
	v_fma_f32 v67, v2, v132, v66
	v_exp_f32_e32 v2, v0
	v_fma_f32 v50, v50, v132, v122
	v_fma_f32 v51, v51, v71, v122
	v_fma_f32 v52, v52, v72, v122
	v_add_f32_e32 v2, 1.0, v2
	v_rcp_f32_e32 v2, v2
	v_fma_f32 v53, v53, v73, v122
	v_fma_f32 v54, v54, v74, v122
	v_fma_f32 v55, v55, v75, v122
	v_fma_f32 v56, v56, v89, v122
	v_fma_f32 v57, v57, v91, v122
	v_fma_f32 v58, v58, v123, v122
	v_fma_f32 v59, v59, v125, v122
	v_fma_f32 v60, v60, v69, v122
	v_fma_f32 v61, v61, v127, v122
	v_fma_f32 v62, v62, v129, v122
	v_fmac_f32_e32 v122, v63, v131
	v_fma_f32 v17, v17, v70, v126
	v_fma_f32 v63, v1, v70, v66
	v_fma_f32 v70, v3, v71, v66
	v_mul_f32_e32 v3, 0xbfb8aa3b, v49
	v_exp_f32_e32 v3, v3
	v_mul_f32_e32 v2, v48, v2
	v_mul_f32_e32 v2, v16, v2
	v_fma_f32 v19, v19, v71, v126
	v_fma_f32 v71, v4, v72, v66
	v_cvt_pk_bf16_f32 v4, v2, s0
	v_add_f32_e32 v2, 1.0, v3
	v_fma_f32 v20, v20, v72, v126
	v_fma_f32 v72, v5, v73, v66
	v_lshl_or_b32 v0, s76, 6, v92
	v_rcp_f32_e32 v5, v2
	v_ashrrev_i32_e32 v1, 31, v0
	v_lshl_add_u64 v[0:1], v[0:1], 1, s[8:9]
	v_mad_i64_i32 v[2:3], s[58:59], v82, s68, v[0:1]
	global_store_short v[2:3], v4, off sc1
	v_mul_f32_e32 v4, v49, v5
	v_mul_f32_e32 v5, 0xbfb8aa3b, v50
	v_fma_f32 v21, v21, v73, v126
	v_fma_f32 v73, v6, v74, v66
	v_exp_f32_e32 v6, v5
	v_mul_f32_e32 v4, v17, v4
	v_fma_f32 v22, v22, v74, v126
	v_fma_f32 v74, v7, v75, v66
	v_add_f32_e32 v6, 1.0, v6
	v_cvt_pk_bf16_f32 v7, v4, s0
	v_mad_i64_i32 v[4:5], s[58:59], v120, s68, v[0:1]
	v_rcp_f32_e32 v6, v6
	global_store_short v[4:5], v7, off sc1
	v_mul_f32_e32 v7, 0xbfb8aa3b, v51
	v_exp_f32_e32 v7, v7
	v_fma_f32 v18, v18, v132, v126
	v_mul_f32_e32 v6, v50, v6
	v_mul_f32_e32 v6, v18, v6
	v_fma_f32 v23, v23, v75, v126
	v_fma_f32 v75, v8, v89, v66
	v_cvt_pk_bf16_f32 v8, v6, s0
	v_add_f32_e32 v6, 1.0, v7
	v_fma_f32 v24, v24, v89, v126
	v_fma_f32 v89, v9, v91, v66
	v_rcp_f32_e32 v9, v6
	v_mad_i64_i32 v[6:7], s[58:59], v119, s68, v[0:1]
	global_store_short v[6:7], v8, off sc1
	v_mul_f32_e32 v8, v51, v9
	v_mul_f32_e32 v9, 0xbfb8aa3b, v52
	v_fma_f32 v25, v25, v91, v126
	v_fma_f32 v91, v10, v123, v66
	v_exp_f32_e32 v10, v9
	v_mul_f32_e32 v8, v19, v8
	v_fma_f32 v26, v26, v123, v126
	v_fma_f32 v123, v11, v125, v66
	v_add_f32_e32 v10, 1.0, v10
	v_cvt_pk_bf16_f32 v11, v8, s0
	v_mad_i64_i32 v[8:9], s[58:59], v83, s68, v[0:1]
	v_rcp_f32_e32 v10, v10
	global_store_short v[8:9], v11, off sc1
	v_mul_f32_e32 v11, 0xbfb8aa3b, v53
	v_exp_f32_e32 v11, v11
	v_mul_f32_e32 v10, v52, v10
	v_mul_f32_e32 v10, v20, v10
	v_fma_f32 v28, v28, v69, v126
	v_fma_f32 v69, v12, v69, v66
	v_cvt_pk_bf16_f32 v12, v10, s0
	v_add_f32_e32 v10, 1.0, v11
	v_fma_f32 v27, v27, v125, v126
	v_fma_f32 v125, v13, v127, v66
	v_rcp_f32_e32 v13, v10
	v_mad_i64_i32 v[10:11], s[58:59], v84, s68, v[0:1]
	global_store_short v[10:11], v12, off sc1
	v_mul_f32_e32 v12, v53, v13
	v_mul_f32_e32 v13, 0xbfb8aa3b, v54
	v_fma_f32 v29, v29, v127, v126
	v_fma_f32 v127, v14, v129, v66
	v_exp_f32_e32 v14, v13
	v_mul_f32_e32 v12, v21, v12
	v_fmac_f32_e32 v66, v15, v131
	v_cvt_pk_bf16_f32 v15, v12, s0
	v_add_f32_e32 v14, 1.0, v14
	v_mad_i64_i32 v[12:13], s[58:59], v68, s68, v[0:1]
	v_rcp_f32_e32 v14, v14
	global_store_short v[12:13], v15, off sc1
	v_mul_f32_e32 v15, 0xbfb8aa3b, v55
	v_exp_f32_e32 v15, v15
	v_mul_f32_e32 v14, v54, v14
	v_mul_f32_e32 v14, v22, v14
	v_cvt_pk_bf16_f32 v16, v14, s0
	v_add_f32_e32 v14, 1.0, v15
	v_rcp_f32_e32 v17, v14
	v_mad_i64_i32 v[14:15], s[58:59], v85, s68, v[0:1]
	global_store_short v[14:15], v16, off sc1
	v_mul_f32_e32 v16, v55, v17
	v_mul_f32_e32 v17, 0xbfb8aa3b, v56
	v_exp_f32_e32 v18, v17
	v_mul_f32_e32 v16, v23, v16
	v_cvt_pk_bf16_f32 v19, v16, s0
	v_mad_i64_i32 v[16:17], s[58:59], v87, s68, v[0:1]
	v_add_f32_e32 v18, 1.0, v18
	v_rcp_f32_e32 v18, v18
	global_store_short v[16:17], v19, off sc1
	v_mul_f32_e32 v19, 0xbfb8aa3b, v57
	v_exp_f32_e32 v19, v19
	v_mul_f32_e32 v18, v56, v18
	v_mul_f32_e32 v18, v24, v18
	v_cvt_pk_bf16_f32 v20, v18, s0
	v_add_f32_e32 v18, 1.0, v19
	v_rcp_f32_e32 v21, v18
	v_mad_i64_i32 v[18:19], s[58:59], v64, s68, v[0:1]
	global_store_short v[18:19], v20, off sc1
	v_mul_f32_e32 v20, v57, v21
	v_mul_f32_e32 v21, 0xbfb8aa3b, v58
	v_exp_f32_e32 v22, v21
	v_mul_f32_e32 v20, v25, v20
	v_cvt_pk_bf16_f32 v23, v20, s0
	v_mad_i64_i32 v[20:21], s[58:59], v88, s68, v[0:1]
	v_add_f32_e32 v22, 1.0, v22
	v_rcp_f32_e32 v22, v22
	global_store_short v[20:21], v23, off sc1
	v_mul_f32_e32 v23, 0xbfb8aa3b, v59
	v_exp_f32_e32 v23, v23
	v_mul_f32_e32 v22, v58, v22
	v_mul_f32_e32 v22, v26, v22
	v_cvt_pk_bf16_f32 v24, v22, s0
	v_add_f32_e32 v22, 1.0, v23
	v_rcp_f32_e32 v25, v22
	v_mad_i64_i32 v[22:23], s[58:59], v121, s68, v[0:1]
	global_store_short v[22:23], v24, off sc1
	v_mul_f32_e32 v24, v59, v25
	v_mul_f32_e32 v25, 0xbfb8aa3b, v60
	v_exp_f32_e32 v26, v25
	v_mul_f32_e32 v24, v27, v24
	v_cvt_pk_bf16_f32 v27, v24, s0
	v_mad_i64_i32 v[24:25], s[58:59], v124, s68, v[0:1]
	v_add_f32_e32 v26, 1.0, v26
	v_rcp_f32_e32 v26, v26
	global_store_short v[24:25], v27, off sc1
	v_mul_f32_e32 v27, 0xbfb8aa3b, v61
	v_exp_f32_e32 v27, v27
	v_mul_f32_e32 v26, v60, v26
	v_mul_f32_e32 v26, v28, v26
	v_cvt_pk_bf16_f32 v28, v26, s0
	v_add_f32_e32 v26, 1.0, v27
	v_fma_f32 v30, v30, v129, v126
	v_fmac_f32_e32 v126, v31, v131
	v_rcp_f32_e32 v31, v26
	v_mad_i64_i32 v[26:27], s[58:59], v86, s68, v[0:1]
	global_store_short v[26:27], v28, off sc1
	v_mul_f32_e32 v28, v61, v31
	v_mul_f32_e32 v28, v29, v28
	v_mul_f32_e32 v29, 0xbfb8aa3b, v62
	v_exp_f32_e32 v31, v29
	v_cvt_pk_bf16_f32 v48, v28, s0
	v_mad_i64_i32 v[28:29], s[58:59], v90, s68, v[0:1]
	v_add_f32_e32 v31, 1.0, v31
	v_rcp_f32_e32 v31, v31
	global_store_short v[28:29], v48, off sc1
	v_mul_f32_e32 v48, 0xbfb8aa3b, v122
	v_exp_f32_e32 v48, v48
	v_mul_f32_e32 v31, v62, v31
	v_mul_f32_e32 v30, v30, v31
	v_cvt_pk_bf16_f32 v49, v30, s0
	v_add_f32_e32 v30, 1.0, v48
	v_rcp_f32_e32 v48, v30
	v_mad_i64_i32 v[30:31], s[58:59], v128, s68, v[0:1]
	global_store_short v[30:31], v49, off sc1
	v_mul_f32_e32 v49, 0xbfb8aa3b, v32
	v_exp_f32_e32 v49, v49
	v_mul_f32_e32 v48, v122, v48
	v_mul_f32_e32 v48, v126, v48
	v_cvt_pk_bf16_f32 v48, v48, s0
	v_mad_i64_i32 v[0:1], s[58:59], v130, s68, v[0:1]
	v_add_f32_e32 v49, 1.0, v49
	v_rcp_f32_e32 v49, v49
	global_store_short v[0:1], v48, off sc1
	v_mul_f32_e32 v48, 0xbfb8aa3b, v33
	v_exp_f32_e32 v48, v48
	v_mul_f32_e32 v32, v32, v49
	v_mul_f32_e32 v32, v47, v32
	v_cvt_pk_bf16_f32 v32, v32, s0
	v_add_f32_e32 v47, 1.0, v48
	v_rcp_f32_e32 v47, v47
	global_store_short v[2:3], v32, off offset:64 sc1
	v_mul_f32_e32 v2, 0xbfb8aa3b, v34
	v_exp_f32_e32 v2, v2
	v_mul_f32_e32 v3, v33, v47
	v_mul_f32_e32 v3, v63, v3
	v_cvt_pk_bf16_f32 v3, v3, s0
	global_store_short v[4:5], v3, off offset:64 sc1
	v_mul_f32_e32 v3, 0xbfb8aa3b, v35
	v_exp_f32_e32 v3, v3
	v_add_f32_e32 v2, 1.0, v2
	v_rcp_f32_e32 v2, v2
	v_mul_f32_e32 v4, 0xbfb8aa3b, v46
	v_add_f32_e32 v3, 1.0, v3
	v_rcp_f32_e32 v3, v3
	v_mul_f32_e32 v2, v34, v2
	v_mul_f32_e32 v2, v67, v2
	v_cvt_pk_bf16_f32 v2, v2, s0
	global_store_short v[6:7], v2, off offset:64 sc1
	v_mul_f32_e32 v2, 0xbfb8aa3b, v36
	v_mul_f32_e32 v3, v35, v3
	v_exp_f32_e32 v2, v2
	v_mul_f32_e32 v3, v70, v3
	v_cvt_pk_bf16_f32 v3, v3, s0
	global_store_short v[8:9], v3, off offset:64 sc1
	v_mul_f32_e32 v3, 0xbfb8aa3b, v37
	v_exp_f32_e32 v3, v3
	v_add_f32_e32 v2, 1.0, v2
	v_rcp_f32_e32 v2, v2
	v_exp_f32_e32 v4, v4
	v_add_f32_e32 v3, 1.0, v3
	v_rcp_f32_e32 v3, v3
	v_mul_f32_e32 v2, v36, v2
	v_mul_f32_e32 v2, v71, v2
	v_cvt_pk_bf16_f32 v2, v2, s0
	global_store_short v[10:11], v2, off offset:64 sc1
	v_mul_f32_e32 v2, 0xbfb8aa3b, v38
	v_mul_f32_e32 v3, v37, v3
	v_exp_f32_e32 v2, v2
	v_mul_f32_e32 v3, v72, v3
	v_cvt_pk_bf16_f32 v3, v3, s0
	global_store_short v[12:13], v3, off offset:64 sc1
	v_mul_f32_e32 v3, 0xbfb8aa3b, v39
	v_exp_f32_e32 v3, v3
	v_add_f32_e32 v2, 1.0, v2
	v_rcp_f32_e32 v2, v2
	v_add_f32_e32 v3, 1.0, v3
	v_rcp_f32_e32 v3, v3
	v_mul_f32_e32 v2, v38, v2
	v_mul_f32_e32 v2, v73, v2
	v_cvt_pk_bf16_f32 v2, v2, s0
	global_store_short v[14:15], v2, off offset:64 sc1
	v_mul_f32_e32 v2, 0xbfb8aa3b, v40
	v_mul_f32_e32 v3, v39, v3
	v_exp_f32_e32 v2, v2
	v_mul_f32_e32 v3, v74, v3
	v_cvt_pk_bf16_f32 v3, v3, s0
	global_store_short v[16:17], v3, off offset:64 sc1
	v_mul_f32_e32 v3, 0xbfb8aa3b, v41
	v_exp_f32_e32 v3, v3
	v_add_f32_e32 v2, 1.0, v2
	v_rcp_f32_e32 v2, v2
	v_add_f32_e32 v3, 1.0, v3
	v_rcp_f32_e32 v3, v3
	v_mul_f32_e32 v2, v40, v2
	v_mul_f32_e32 v2, v75, v2
	v_cvt_pk_bf16_f32 v2, v2, s0
	global_store_short v[18:19], v2, off offset:64 sc1
	v_mul_f32_e32 v2, 0xbfb8aa3b, v42
	v_mul_f32_e32 v3, v41, v3
	v_exp_f32_e32 v2, v2
	v_mul_f32_e32 v3, v89, v3
	v_cvt_pk_bf16_f32 v3, v3, s0
	global_store_short v[20:21], v3, off offset:64 sc1
	v_mul_f32_e32 v3, 0xbfb8aa3b, v43
	v_exp_f32_e32 v3, v3
	v_add_f32_e32 v2, 1.0, v2
	v_rcp_f32_e32 v2, v2
	v_add_f32_e32 v3, 1.0, v3
	v_rcp_f32_e32 v3, v3
	v_mul_f32_e32 v2, v42, v2
	v_mul_f32_e32 v2, v91, v2
	v_cvt_pk_bf16_f32 v2, v2, s0
	global_store_short v[22:23], v2, off offset:64 sc1
	v_mul_f32_e32 v2, 0xbfb8aa3b, v44
	v_mul_f32_e32 v3, v43, v3
	v_exp_f32_e32 v2, v2
	v_mul_f32_e32 v3, v123, v3
	v_cvt_pk_bf16_f32 v3, v3, s0
	global_store_short v[24:25], v3, off offset:64 sc1
	v_mul_f32_e32 v3, 0xbfb8aa3b, v45
	v_exp_f32_e32 v3, v3
	v_add_f32_e32 v2, 1.0, v2
	v_rcp_f32_e32 v2, v2
	v_add_f32_e32 v3, 1.0, v3
	v_rcp_f32_e32 v3, v3
	v_mul_f32_e32 v2, v44, v2
	v_mul_f32_e32 v2, v69, v2
	v_cvt_pk_bf16_f32 v2, v2, s0
	global_store_short v[26:27], v2, off offset:64 sc1
	v_mul_f32_e32 v2, v45, v3
	v_add_f32_e32 v3, 1.0, v4
	v_mul_f32_e32 v4, 0xbfb8aa3b, v65
	v_rcp_f32_e32 v3, v3
	v_exp_f32_e32 v4, v4
	v_mul_f32_e32 v2, v125, v2
	v_cvt_pk_bf16_f32 v2, v2, s0
	global_store_short v[28:29], v2, off offset:64 sc1
	v_mul_f32_e32 v2, v46, v3
	v_add_f32_e32 v3, 1.0, v4
	v_rcp_f32_e32 v3, v3
	v_mul_f32_e32 v2, v127, v2
	v_cvt_pk_bf16_f32 v2, v2, s0
	global_store_short v[30:31], v2, off offset:64 sc1
	v_mul_f32_e32 v2, v65, v3
	v_mul_f32_e32 v2, v66, v2
	v_cvt_pk_bf16_f32 v2, v2, s0
	global_store_short v[0:1], v2, off offset:64 sc1
	s_cbranch_scc1 .LBB0_759

.Lgk_pfhead_p7:
	v_and_b32_e32 v152, 31, v199
	v_bfe_u32 v153, v199, 5, 1
	v_lshlrev_b32_e32 v154, 2, v153
	v_sub_u32_e32 v152, v152, v154
	v_add_u32_e32 v154, s60, v93
	v_add_lshl_u32 v152, v152, v154, 2
	v_lshlrev_b32_e32 v153, 4, v153
	global_load_dword v144, v152, s[6:7]
	v_add_u32_e32 v154, 0x10000, v152
	global_load_dword v145, v154, s[6:7]
	v_add_u32_e32 v154, 0x20000, v152
	global_load_dword v146, v154, s[6:7]
	v_add_u32_e32 v154, 0x30000, v152
	global_load_dword v147, v154, s[6:7]
	v_add_u32_e32 v154, 0x40000, v152
	global_load_dword v148, v154, s[6:7]
	v_add_u32_e32 v154, 0x50000, v152
	global_load_dword v149, v154, s[6:7]
	v_add_u32_e32 v154, 0x60000, v152
	global_load_dword v150, v154, s[6:7]
	v_add_u32_e32 v154, 0x70000, v152
	global_load_dword v151, v154, s[6:7]
	s_add_i32 s59, s60, 0xffffe000
	s_lshr_b32 s59, s59, 12
	s_mulk_i32 s59, 0x1600
	s_addk_i32 s59, 0x1600
	s_cmp_gt_i32 s4, 63
	s_cselect_b32 s59, s59, 0
	v_or_b32_e32 v154, s58, v92
	v_add_lshl_u32 v154, v154, s59, 2
	global_load_dword v172, v154, s[10:11]
	global_load_dword v173, v154, s[10:11] offset:128
	global_load_dword v174, v154, s[10:11] offset:256
	global_load_dword v175, v154, s[10:11] offset:384
	v_mov_b32_e32 v48, 0
	v_mov_b32_e32 v49, 0
	v_mov_b32_e32 v50, 0
	v_mov_b32_e32 v51, 0
	v_mov_b32_e32 v52, 0
	v_mov_b32_e32 v53, 0
	v_mov_b32_e32 v54, 0
	v_mov_b32_e32 v55, 0
	v_mov_b32_e32 v56, 0
	v_mov_b32_e32 v57, 0
	v_mov_b32_e32 v58, 0
	v_mov_b32_e32 v59, 0
	v_mov_b32_e32 v60, 0
	v_mov_b32_e32 v61, 0
	v_mov_b32_e32 v62, 0
	v_mov_b32_e32 v63, 0
	v_mov_b32_e32 v32, 0
	v_mov_b32_e32 v33, 0
	v_mov_b32_e32 v34, 0
	v_mov_b32_e32 v35, 0
	v_mov_b32_e32 v36, 0
	v_mov_b32_e32 v37, 0
	v_mov_b32_e32 v38, 0
	v_mov_b32_e32 v39, 0
	v_mov_b32_e32 v40, 0
	v_mov_b32_e32 v41, 0
	v_mov_b32_e32 v42, 0
	v_mov_b32_e32 v43, 0
	v_mov_b32_e32 v44, 0
	v_mov_b32_e32 v45, 0
	v_mov_b32_e32 v46, 0
	v_mov_b32_e32 v47, 0
	v_mov_b32_e32 v16, 0
	v_mov_b32_e32 v17, 0
	v_mov_b32_e32 v18, 0
	v_mov_b32_e32 v19, 0
	v_mov_b32_e32 v20, 0
	v_mov_b32_e32 v21, 0
	v_mov_b32_e32 v22, 0
	v_mov_b32_e32 v23, 0
	v_mov_b32_e32 v24, 0
	v_mov_b32_e32 v25, 0
	v_mov_b32_e32 v26, 0
	v_mov_b32_e32 v27, 0
	v_mov_b32_e32 v28, 0
	v_mov_b32_e32 v29, 0
	v_mov_b32_e32 v30, 0
	v_mov_b32_e32 v31, 0
	v_mov_b32_e32 v0, 0
	v_mov_b32_e32 v1, 0
	v_mov_b32_e32 v2, 0
	v_mov_b32_e32 v3, 0
	v_mov_b32_e32 v4, 0
	v_mov_b32_e32 v5, 0
	v_mov_b32_e32 v6, 0
	v_mov_b32_e32 v7, 0
	v_mov_b32_e32 v8, 0
	v_mov_b32_e32 v9, 0
	v_mov_b32_e32 v10, 0
	v_mov_b32_e32 v11, 0
	v_mov_b32_e32 v12, 0
	v_mov_b32_e32 v13, 0
	v_mov_b32_e32 v14, 0
	v_mov_b32_e32 v15, 0
	s_mov_b32 s37, 7
